# v26 + same z-row direct-load edit in the NSA sliding-window loop
# baseline (speedup 1.0000x reference)
; DI void nsa_unit(const bf16* PR, const float* AUX, const bf16* KC, const bf16* VC, bf16* MIX, char* sm, int b, int qb) {
;     ...
;         for (int it_ = -1, nt_ = (cur - j0 + 1); it_ < nt_; ++it_) {
;         const bool more_ = it_ + 1 < nt_;
;         if (!more_) { const bf16* zrow0 = PR + (rb + 64 * qb + 32 * (wid & 1)) * NP + C_NZ + 64 * g;
; #pragma unroll
;             for (int j = 0; j < 2; ++j) zpre[j] = *(const u32x4*)(zrow0 + (size_t)((lane >> 3) + 8 * j) * NP + 8 * (lane & 7)); }
.LBB0_531:
	s_add_i32 s18, s17, 8
	s_cmp_lt_i32 s18, s12
	s_cselect_b64 s[6:7], -1, 0
	s_mov_b64 s[0:1], -1
	s_and_b64 vcc, exec, s[6:7]
	s_cbranch_vccnz .LBB0_533
	global_load_dwordx4 v[104:107], v[146:147], off
	global_load_dwordx4 v[100:103], v[158:159], off
	s_mov_b64 s[0:1], 0

; DI void nsa_unit(const bf16* PR, const float* AUX, const bf16* KC, const bf16* VC, bf16* MIX, char* sm, int b, int qb) {
;     ...
;         for (int it_ = -1, nt_ = (cur - j0 + 1); it_ < nt_; ++it_) {
;         const bool more_ = it_ + 1 < nt_;
;         if (!more_) { const bf16* zrow0 = PR + (rb + 64 * qb + 32 * (wid & 1)) * NP + C_NZ + 64 * g;
; #pragma unroll
;             for (int j = 0; j < 2; ++j) zpre[j] = *(const u32x4*)(zrow0 + (size_t)((lane >> 3) + 8 * j) * NP + 8 * (lane & 7)); }
;         if (more_) { const int it = it_ + 1; { const int j = cur - it; kv_issue(Kb + (size_t)(64 * j) * NP, Vb + (size_t)(64 * j) * NP, NP, wid, lane, kr, vr); if (wid == 0) ar = pos_aug(64 * j + lane); } }
;         if (it_ >= 0) { const int it = it_; const char* cb = sm + (it & 1) * STG; { const int j = cur - it;
.LBB0_542:
	s_cmp_lt_i32 s18, 0
	s_cbranch_scc0 .LBB0_537

; DI float bf2f(unsigned h) { return __uint_as_float(h << 16); }
; DI unsigned cvtpk(float lo, float hi) { f32x2_t v = {lo, hi}; bf16x2_t b = __builtin_convertvector(v, bf16x2_t); return __builtin_bit_cast(unsigned, b); }
; DI float silu_f(float z) { return z * sigm_f(z); }
; DI void write_out_zh(const f32x16& o0, const f32x16& o1, float sc, const u32x4 (&zpre)[2], const bf16* zrow0, size_t zpitch, bf16* orow0, size_t opitch, float* st, int lane) {
;     const int q = lane & 31, hi = lane >> 5;
; #pragma unroll
;     for (int d0 = 0; d0 < 2; ++d0)
; #pragma unroll
;         for (int gq = 0; gq < 4; ++gq) {
;             const int ch = 8 * d0 + 2 * gq + hi; const f32x16& o = d0 ? o1 : o0;
;             *(f32x4*)(st + q * 64 + ((ch ^ (q & 15)) << 2)) = (f32x4){o[4 * gq] * sc, o[4 * gq + 1] * sc, o[4 * gq + 2] * sc, o[4 * gq + 3] * sc};
;         }
; #pragma unroll
;     for (int j = 0; j < 4; ++j) {
;         const int row = (lane >> 3) + 8 * j, c = lane & 7;
;         const f32x4 a = *(const f32x4*)(st + row * 64 + (((2 * c) ^ (row & 15)) << 2)), b = *(const f32x4*)(st + row * 64 + (((2 * c + 1) ^ (row & 15)) << 2));
;         const u32x4 zz = j < 2 ? zpre[j & 1] : *(const u32x4*)(zrow0 + (size_t)row * zpitch + 8 * c);
;         u32x4 w;
;         w.x = cvtpk(a[0] * silu_f(bf2f(zz.x & 0xffffu)), a[1] * silu_f(bf2f(zz.x >> 16)));
;         w.y = cvtpk(a[2] * silu_f(bf2f(zz.y & 0xffffu)), a[3] * silu_f(bf2f(zz.y >> 16)));
;         w.z = cvtpk(b[0] * silu_f(bf2f(zz.z & 0xffffu)), b[1] * silu_f(bf2f(zz.z >> 16)));
;         w.w = cvtpk(b[2] * silu_f(bf2f(zz.w & 0xffffu)), b[3] * silu_f(bf2f(zz.w >> 16)));
;         *(u32x4*)(orow0 + (size_t)row * opitch + 8 * c) = w;
;     }
; DI void nsa_unit(const bf16* PR, const float* AUX, const bf16* KC, const bf16* VC, bf16* MIX, char* sm, int b, int qb) {
;     ...
;         const float lt = l + __shfl_xor(l, 32); const float sc = lt > 0.f ? g2 / lt : 0.f;
; #pragma unroll
;         for (int i = 0; i < 16; ++i) { o0[i] = tacc[i * 64] + sc * o0[i]; o1[i] = tacc[(16 + i) * 64] + sc * o1[i]; }
.LBB0_548:
	s_waitcnt vmcnt(0)
	v_mul_f32_e32 v0, 0xbfb8aa3b, v140
	v_exp_f32_e32 v0, v0
	ds_bpermute_b32 v2, v212, v223
	v_add_f32_e32 v0, 1.0, v0
	v_rcp_f32_e32 v0, v0
	s_waitcnt lgkmcnt(0)
	v_add_f32_e32 v38, v223, v2
	ds_read2st64_b32 v[2:3], v217 offset1:1
	ds_read2st64_b32 v[36:37], v217 offset0:2 offset1:3
	v_div_scale_f32 v39, s[0:1], v38, v38, v0
	s_waitcnt vmcnt(2)
	v_rcp_f32_e32 v40, v39
	v_div_scale_f32 v41, vcc, v0, v38, v0
	s_lshl_b64 s[0:1], s[8:9], 11
	v_fma_f32 v42, -v39, v40, 1.0
	v_fmac_f32_e32 v40, v42, v40
	v_mul_f32_e32 v42, v41, v40
	v_fma_f32 v43, -v39, v42, v41
	v_fmac_f32_e32 v42, v43, v40
	v_fma_f32 v39, -v39, v42, v41
	v_div_fmas_f32 v39, v39, v40, v42
	v_div_fixup_f32 v0, v39, v38, v0
	v_cmp_lt_f32_e32 vcc, 0, v38
	ds_read2st64_b32 v[38:39], v217 offset0:16 offset1:17
	ds_read2st64_b32 v[40:41], v217 offset0:18 offset1:19
	ds_read2st64_b32 v[42:43], v217 offset0:4 offset1:5
	ds_read2st64_b32 v[44:45], v217 offset0:6 offset1:7
	v_cndmask_b32_e32 v0, 0, v0, vcc
	s_waitcnt lgkmcnt(4)
	v_pk_fma_f32 v[22:23], v[22:23], v[0:1], v[36:37] op_sel_hi:[1,0,1]
	ds_read2st64_b32 v[36:37], v217 offset0:20 offset1:21
	ds_read2st64_b32 v[46:47], v217 offset0:22 offset1:23
	v_pk_fma_f32 v[20:21], v[20:21], v[0:1], v[2:3] op_sel_hi:[1,0,1]
	s_waitcnt lgkmcnt(5)
	v_pk_fma_f32 v[2:3], v[4:5], v[0:1], v[38:39] op_sel_hi:[1,0,1]
	s_waitcnt lgkmcnt(4)
	v_pk_fma_f32 v[4:5], v[6:7], v[0:1], v[40:41] op_sel_hi:[1,0,1]
	s_waitcnt lgkmcnt(3)
	v_pk_fma_f32 v[6:7], v[24:25], v[0:1], v[42:43] op_sel_hi:[1,0,1]
	s_waitcnt lgkmcnt(1)
	v_pk_fma_f32 v[24:25], v[8:9], v[0:1], v[36:37] op_sel_hi:[1,0,1]
	v_pk_fma_f32 v[8:9], v[26:27], v[0:1], v[44:45] op_sel_hi:[1,0,1]
	s_waitcnt lgkmcnt(0)
	v_pk_fma_f32 v[26:27], v[10:11], v[0:1], v[46:47] op_sel_hi:[1,0,1]
	ds_read2st64_b32 v[10:11], v217 offset0:8 offset1:9
	ds_read2st64_b32 v[36:37], v217 offset0:24 offset1:25
	ds_read2st64_b32 v[38:39], v217 offset0:10 offset1:11
	ds_read2st64_b32 v[40:41], v217 offset0:12 offset1:13
	ds_read2st64_b32 v[42:43], v217 offset0:14 offset1:15
	ds_read2st64_b32 v[44:45], v217 offset0:26 offset1:27
	ds_read2st64_b32 v[46:47], v217 offset0:28 offset1:29
	ds_read2st64_b32 v[48:49], v217 offset0:30 offset1:31
	s_waitcnt lgkmcnt(7)
	v_pk_fma_f32 v[10:11], v[28:29], v[0:1], v[10:11] op_sel_hi:[1,0,1]
	s_waitcnt lgkmcnt(6)
	v_pk_fma_f32 v[28:29], v[12:13], v[0:1], v[36:37] op_sel_hi:[1,0,1]
	s_waitcnt lgkmcnt(5)
	v_pk_fma_f32 v[12:13], v[30:31], v[0:1], v[38:39] op_sel_hi:[1,0,1]
	s_waitcnt lgkmcnt(2)
	v_pk_fma_f32 v[30:31], v[14:15], v[0:1], v[44:45] op_sel_hi:[1,0,1]
	v_pk_fma_f32 v[14:15], v[32:33], v[0:1], v[40:41] op_sel_hi:[1,0,1]
	s_waitcnt lgkmcnt(1)
	v_pk_fma_f32 v[32:33], v[16:17], v[0:1], v[46:47] op_sel_hi:[1,0,1]
	v_pk_fma_f32 v[16:17], v[34:35], v[0:1], v[42:43] op_sel_hi:[1,0,1]
	s_waitcnt lgkmcnt(0)
	v_pk_fma_f32 v[34:35], v[18:19], v[0:1], v[48:49] op_sel_hi:[1,0,1]
	v_and_b32_e32 v0, 0x7c0, v162
	v_lshl_add_u32 v0, v0, 2, s16
	v_bitop3_b32 v19, v160, v161, 15 bitop3:0x78
	v_and_b32_e32 v18, 15, v161
	v_lshl_add_u32 v19, v19, 4, v0
	ds_write_b128 v19, v[20:23]
	v_bitop3_b32 v19, v160, v18, 2 bitop3:0x36
	v_lshl_add_u32 v19, v19, 4, v0
	ds_write_b128 v19, v[6:9]
	v_bitop3_b32 v6, v160, v18, 4 bitop3:0x36
	v_lshl_add_u32 v6, v6, 4, v0
	ds_write_b128 v6, v[10:13]
	v_bitop3_b32 v6, v160, v18, 6 bitop3:0x36
	v_lshl_add_u32 v6, v6, 4, v0
	ds_write_b128 v6, v[14:17]
	v_bitop3_b32 v6, v160, v18, 8 bitop3:0x36
	v_lshl_add_u32 v6, v6, 4, v0
	ds_write_b128 v6, v[2:5]
	v_bitop3_b32 v2, v160, v18, 10 bitop3:0x36
	v_lshl_add_u32 v2, v2, 4, v0
	ds_write_b128 v2, v[24:27]
	v_bitop3_b32 v2, v160, v18, 12 bitop3:0x36
	v_lshl_add_u32 v2, v2, 4, v0
	ds_write_b128 v2, v[28:31]
	v_bitop3_b32 v2, v160, v18, 14 bitop3:0x36
	v_lshrrev_b32_e32 v30, 3, v149
	v_lshlrev_b32_e32 v31, 1, v218
	s_add_u32 s0, s96, s0
	v_lshl_add_u32 v0, v2, 4, v0
	v_bitop3_b32 v7, v31, v30, 1 bitop3:0x36
	v_lshlrev_b32_e32 v14, 16, v104
	s_addc_u32 s1, s97, s1
	ds_write_b128 v0, v[32:35]
	v_lshlrev_b32_e32 v34, 4, v7
	v_and_b32_e32 v15, 0xffff0000, v104
	v_mul_f32_e32 v7, 0xbfb8aa3b, v14
	s_add_u32 s0, s0, s14
	v_exp_f32_e32 v16, v7
	v_mul_f32_e32 v7, 0xbfb8aa3b, v15
	s_addc_u32 s1, s1, s15
	v_lshlrev_b32_e32 v0, 4, v218
	v_xor_b32_e32 v6, v30, v31
	v_exp_f32_e32 v17, v7
	v_lshl_add_u64 v[2:3], s[0:1], 0, v[0:1]
	v_lshl_add_u64 v[4:5], s[4:5], 0, v[0:1]
	v_lshl_add_u32 v0, v30, 8, s16
	v_lshlrev_b32_e32 v33, 4, v6
	v_add_u32_e32 v6, v0, v33
	v_add_u32_e32 v0, v0, v34
	ds_read_b128 v[6:9], v6
	ds_read_b128 v[10:13], v0
	v_add_f32_e32 v0, 1.0, v16
	v_lshlrev_b32_e32 v18, 16, v105
	v_rcp_f32_e32 v16, v0
	v_add_f32_e32 v0, 1.0, v17
	v_and_b32_e32 v19, 0xffff0000, v105
	v_mul_f32_e32 v17, 0xbfb8aa3b, v18
	v_exp_f32_e32 v20, v17
	v_mul_f32_e32 v17, 0xbfb8aa3b, v19
	v_exp_f32_e32 v21, v17
	v_rcp_f32_e32 v17, v0
	v_add_f32_e32 v0, 1.0, v20
	v_rcp_f32_e32 v20, v0
	v_add_f32_e32 v0, 1.0, v21
	v_rcp_f32_e32 v21, v0
	v_pk_mul_f32 v[14:15], v[16:17], v[14:15]
	v_or_b32_e32 v28, 8, v30
	s_waitcnt lgkmcnt(1)
	v_pk_mul_f32 v[6:7], v[14:15], v[6:7]
	v_pk_mul_f32 v[14:15], v[20:21], v[18:19]
	v_lshlrev_b32_e32 v18, 16, v106
	v_mul_f32_e32 v0, 0xbfb8aa3b, v18
	v_exp_f32_e32 v0, v0
	v_pk_mul_f32 v[8:9], v[14:15], v[8:9]
	v_and_b32_e32 v19, 0xffff0000, v106
	v_cvt_pk_bf16_f32 v6, v6, v7
	v_add_f32_e32 v0, 1.0, v0
	v_cvt_pk_bf16_f32 v7, v8, v9
	v_rcp_f32_e32 v8, v0
	v_mul_f32_e32 v0, 0xbfb8aa3b, v19
	v_exp_f32_e32 v0, v0
	v_lshlrev_b32_e32 v20, 16, v107
	v_mul_f32_e32 v9, 0xbfb8aa3b, v20
	v_and_b32_e32 v21, 0xffff0000, v107
	v_add_f32_e32 v0, 1.0, v0
	v_exp_f32_e32 v14, v9
	v_rcp_f32_e32 v9, v0
	v_mul_f32_e32 v0, 0xbfb8aa3b, v21
	v_exp_f32_e32 v27, v0
	v_lshlrev_b32_e32 v0, 11, v30
	v_lshl_add_u64 v[22:23], v[2:3], 0, v[0:1]
	v_lshlrev_b32_e32 v0, 11, v28
	v_or_b32_e32 v35, 16, v30
	v_lshl_add_u64 v[24:25], v[2:3], 0, v[0:1]
	v_lshlrev_b32_e32 v0, 13, v35
	v_add_f32_e32 v26, 1.0, v14
	v_lshl_add_u64 v[14:15], v[4:5], 0, v[0:1]
	global_load_dwordx4 v[14:17], v[14:15], off
	v_add_f32_e32 v0, 1.0, v27
	v_rcp_f32_e32 v26, v26
	v_rcp_f32_e32 v27, v0
	v_pk_mul_f32 v[8:9], v[8:9], v[18:19]
	v_or_b32_e32 v32, 1, v31
	s_waitcnt lgkmcnt(0)
; #define LAS __attribute__((address_space(3)))
; DI float bf2f(unsigned h) { return __uint_as_float(h << 16); }
; DI unsigned cvtpk(float lo, float hi) { f32x2_t v = {lo, hi}; bf16x2_t b = __builtin_convertvector(v, bf16x2_t); return __builtin_bit_cast(unsigned, b); }
; DI float silu_f(float z) { return z * sigm_f(z); }
; DI void write_out_zh(const f32x16& o0, const f32x16& o1, float sc, const u32x4 (&zpre)[2], const bf16* zrow0, size_t zpitch, bf16* orow0, size_t opitch, float* st, int lane) {
;     ...
;     for (int j = 0; j < 4; ++j) {
;         const int row = (lane >> 3) + 8 * j, c = lane & 7;
;         const f32x4 a = *(const f32x4*)(st + row * 64 + (((2 * c) ^ (row & 15)) << 2)), b = *(const f32x4*)(st + row * 64 + (((2 * c + 1) ^ (row & 15)) << 2));
;         const u32x4 zz = j < 2 ? zpre[j & 1] : *(const u32x4*)(zrow0 + (size_t)row * zpitch + 8 * c);
;         u32x4 w;
;         w.x = cvtpk(a[0] * silu_f(bf2f(zz.x & 0xffffu)), a[1] * silu_f(bf2f(zz.x >> 16)));
;         w.y = cvtpk(a[2] * silu_f(bf2f(zz.y & 0xffffu)), a[3] * silu_f(bf2f(zz.y >> 16)));
;         w.z = cvtpk(b[0] * silu_f(bf2f(zz.z & 0xffffu)), b[1] * silu_f(bf2f(zz.z >> 16)));
;         w.w = cvtpk(b[2] * silu_f(bf2f(zz.w & 0xffffu)), b[3] * silu_f(bf2f(zz.w >> 16)));
;         *(u32x4*)(orow0 + (size_t)row * opitch + 8 * c) = w;
;     }
; __global__ void __launch_bounds__(512, 2) mega_fwd(Params p) {
;     ...
;             { volatile LAS int* slot = (volatile LAS int*)(sm + L_MISC); __syncthreads(); if (threadIdx.x == 0) *slot = nxt_; __syncthreads(); u = *slot; }
	v_pk_mul_f32 v[8:9], v[8:9], v[10:11]
	v_pk_mul_f32 v[10:11], v[26:27], v[20:21]
	v_cvt_pk_bf16_f32 v8, v8, v9
	v_pk_mul_f32 v[10:11], v[10:11], v[12:13]
	v_lshl_add_u32 v0, v28, 8, s16
	v_cvt_pk_bf16_f32 v9, v10, v11
	global_store_dwordx4 v[22:23], v[6:9], off offset:1536
	v_lshlrev_b32_e32 v18, 16, v100
	v_and_b32_e32 v19, 0xffff0000, v100
	v_bitop3_b32 v6, v30, v31, 8 bitop3:0x36
	v_bitop3_b32 v7, v30, v32, 8 bitop3:0x36
	v_lshl_add_u32 v6, v6, 4, v0
	v_lshl_add_u32 v0, v7, 4, v0
	v_mul_f32_e32 v7, 0xbfb8aa3b, v18
	v_exp_f32_e32 v20, v7
	v_mul_f32_e32 v7, 0xbfb8aa3b, v19
	v_exp_f32_e32 v21, v7
	ds_read_b128 v[6:9], v6
	ds_read_b128 v[10:13], v0
	v_add_f32_e32 v0, 1.0, v20
	v_lshlrev_b32_e32 v22, 16, v101
	v_rcp_f32_e32 v20, v0
	v_add_f32_e32 v0, 1.0, v21
	v_and_b32_e32 v23, 0xffff0000, v101
	v_mul_f32_e32 v21, 0xbfb8aa3b, v22
	v_exp_f32_e32 v26, v21
	v_mul_f32_e32 v21, 0xbfb8aa3b, v23
	v_exp_f32_e32 v27, v21
	v_rcp_f32_e32 v21, v0
	v_add_f32_e32 v0, 1.0, v26
	v_rcp_f32_e32 v26, v0
	v_add_f32_e32 v0, 1.0, v27
	v_rcp_f32_e32 v27, v0
	v_pk_mul_f32 v[18:19], v[20:21], v[18:19]
	v_or_b32_e32 v30, 24, v30
	s_waitcnt lgkmcnt(1)
	v_pk_mul_f32 v[6:7], v[18:19], v[6:7]
	v_pk_mul_f32 v[18:19], v[26:27], v[22:23]
	v_lshlrev_b32_e32 v22, 16, v102
	v_mul_f32_e32 v0, 0xbfb8aa3b, v22
	v_exp_f32_e32 v0, v0
	v_and_b32_e32 v23, 0xffff0000, v102
	v_cvt_pk_bf16_f32 v6, v6, v7
	v_mul_f32_e32 v7, 0xbfb8aa3b, v23
	v_pk_mul_f32 v[8:9], v[18:19], v[8:9]
	v_exp_f32_e32 v18, v7
	v_add_f32_e32 v0, 1.0, v0
	v_cvt_pk_bf16_f32 v7, v8, v9
	v_rcp_f32_e32 v8, v0
	v_lshlrev_b32_e32 v0, 11, v35
	v_lshl_add_u64 v[28:29], v[2:3], 0, v[0:1]
	v_lshlrev_b32_e32 v0, 13, v30
	v_lshl_add_u64 v[4:5], v[4:5], 0, v[0:1]
	v_add_f32_e32 v9, 1.0, v18
	global_load_dwordx4 v[18:21], v[4:5], off
	v_lshlrev_b32_e32 v26, 16, v103
	v_and_b32_e32 v27, 0xffff0000, v103
	v_mul_f32_e32 v0, 0xbfb8aa3b, v26
	v_exp_f32_e32 v0, v0
	v_mul_f32_e32 v4, 0xbfb8aa3b, v27
	v_exp_f32_e32 v5, v4
	v_rcp_f32_e32 v9, v9
	v_add_f32_e32 v0, 1.0, v0
	v_rcp_f32_e32 v4, v0
	v_add_f32_e32 v0, 1.0, v5
	v_rcp_f32_e32 v5, v0
	v_pk_mul_f32 v[8:9], v[8:9], v[22:23]
	v_lshl_add_u32 v0, v35, 8, s16
	s_waitcnt lgkmcnt(0)
	v_pk_mul_f32 v[8:9], v[8:9], v[10:11]
	v_pk_mul_f32 v[4:5], v[4:5], v[26:27]
	v_cvt_pk_bf16_f32 v8, v8, v9
	v_pk_mul_f32 v[4:5], v[4:5], v[12:13]
	s_waitcnt vmcnt(2)
	v_lshlrev_b32_e32 v12, 16, v14
	v_cvt_pk_bf16_f32 v9, v4, v5
	v_and_b32_e32 v13, 0xffff0000, v14
	v_mul_f32_e32 v5, 0xbfb8aa3b, v12
	v_exp_f32_e32 v14, v5
	v_mul_f32_e32 v5, 0xbfb8aa3b, v13
	v_exp_f32_e32 v22, v5
	global_store_dwordx4 v[24:25], v[6:9], off offset:1536
	v_add_u32_e32 v4, v0, v33
	v_add_u32_e32 v0, v0, v34
	ds_read_b128 v[4:7], v4
	ds_read_b128 v[8:11], v0
	v_add_f32_e32 v0, 1.0, v14
	v_rcp_f32_e32 v14, v0
	v_add_f32_e32 v0, 1.0, v22
	v_lshlrev_b32_e32 v22, 16, v15
	v_and_b32_e32 v23, 0xffff0000, v15
	v_mul_f32_e32 v15, 0xbfb8aa3b, v22
	v_exp_f32_e32 v24, v15
	v_mul_f32_e32 v15, 0xbfb8aa3b, v23
	v_exp_f32_e32 v25, v15
	v_rcp_f32_e32 v15, v0
	v_add_f32_e32 v0, 1.0, v24
	v_rcp_f32_e32 v24, v0
	v_add_f32_e32 v0, 1.0, v25
	v_rcp_f32_e32 v25, v0
	v_pk_mul_f32 v[12:13], v[14:15], v[12:13]
	v_and_b32_e32 v15, 0xffff0000, v17
	s_waitcnt lgkmcnt(1)
	v_pk_mul_f32 v[4:5], v[4:5], v[12:13]
	v_pk_mul_f32 v[12:13], v[24:25], v[22:23]
	v_cvt_pk_bf16_f32 v4, v4, v5
	v_pk_mul_f32 v[6:7], v[6:7], v[12:13]
	v_lshlrev_b32_e32 v12, 16, v16
	v_and_b32_e32 v13, 0xffff0000, v16
	v_mul_f32_e32 v0, 0xbfb8aa3b, v12
	v_exp_f32_e32 v0, v0
	v_mul_f32_e32 v5, 0xbfb8aa3b, v13
	v_exp_f32_e32 v14, v5
	v_cvt_pk_bf16_f32 v5, v6, v7
	v_add_f32_e32 v0, 1.0, v0
	v_rcp_f32_e32 v6, v0
	v_add_f32_e32 v0, 1.0, v14
	v_lshlrev_b32_e32 v14, 16, v17
	v_mul_f32_e32 v7, 0xbfb8aa3b, v14
	v_exp_f32_e32 v16, v7
	v_mul_f32_e32 v7, 0xbfb8aa3b, v15
	v_exp_f32_e32 v17, v7
	v_rcp_f32_e32 v7, v0
	v_add_f32_e32 v0, 1.0, v16
	v_rcp_f32_e32 v16, v0
	v_add_f32_e32 v0, 1.0, v17
	v_rcp_f32_e32 v17, v0
	v_pk_mul_f32 v[6:7], v[6:7], v[12:13]
	v_lshl_add_u32 v0, v30, 8, s16
	s_waitcnt lgkmcnt(0)
	v_pk_mul_f32 v[6:7], v[8:9], v[6:7]
	v_pk_mul_f32 v[8:9], v[16:17], v[14:15]
	v_cvt_pk_bf16_f32 v6, v6, v7
	v_pk_mul_f32 v[8:9], v[10:11], v[8:9]
	s_waitcnt vmcnt(1)
	v_lshlrev_b32_e32 v12, 16, v18
	v_cvt_pk_bf16_f32 v7, v8, v9
	global_store_dwordx4 v[28:29], v[4:7], off offset:1536
	v_and_b32_e32 v13, 0xffff0000, v18
	v_lshlrev_b32_e32 v16, 16, v19
	v_bitop3_b32 v4, v30, v31, 15 bitop3:0x6c
	v_bitop3_b32 v5, v30, v32, 15 bitop3:0x6c
	v_lshl_add_u32 v4, v4, 4, v0
	v_lshl_add_u32 v0, v5, 4, v0
	v_mul_f32_e32 v5, 0xbfb8aa3b, v12
	v_exp_f32_e32 v14, v5
	v_mul_f32_e32 v5, 0xbfb8aa3b, v13
	v_exp_f32_e32 v15, v5
	ds_read_b128 v[4:7], v4
	ds_read_b128 v[8:11], v0
	v_add_f32_e32 v0, 1.0, v14
	v_rcp_f32_e32 v14, v0
	v_add_f32_e32 v0, 1.0, v15
	v_and_b32_e32 v17, 0xffff0000, v19
	v_mul_f32_e32 v15, 0xbfb8aa3b, v16
	v_exp_f32_e32 v18, v15
	v_mul_f32_e32 v15, 0xbfb8aa3b, v17
	v_exp_f32_e32 v19, v15
	v_rcp_f32_e32 v15, v0
	v_add_f32_e32 v0, 1.0, v18
	v_rcp_f32_e32 v18, v0
	v_add_f32_e32 v0, 1.0, v19
	v_rcp_f32_e32 v19, v0
	v_pk_mul_f32 v[12:13], v[14:15], v[12:13]
	v_and_b32_e32 v15, 0xffff0000, v21
	s_waitcnt lgkmcnt(1)
	v_pk_mul_f32 v[4:5], v[4:5], v[12:13]
	v_pk_mul_f32 v[12:13], v[18:19], v[16:17]
	v_cvt_pk_bf16_f32 v4, v4, v5
	v_pk_mul_f32 v[6:7], v[6:7], v[12:13]
	v_lshlrev_b32_e32 v12, 16, v20
	v_and_b32_e32 v13, 0xffff0000, v20
	v_mul_f32_e32 v0, 0xbfb8aa3b, v12
	v_exp_f32_e32 v0, v0
	v_mul_f32_e32 v5, 0xbfb8aa3b, v13
	v_exp_f32_e32 v14, v5
	v_cvt_pk_bf16_f32 v5, v6, v7
	v_add_f32_e32 v0, 1.0, v0
	v_rcp_f32_e32 v6, v0
	v_add_f32_e32 v0, 1.0, v14
	v_lshlrev_b32_e32 v14, 16, v21
	v_mul_f32_e32 v7, 0xbfb8aa3b, v14
	v_exp_f32_e32 v16, v7
	v_mul_f32_e32 v7, 0xbfb8aa3b, v15
	v_exp_f32_e32 v17, v7
	v_rcp_f32_e32 v7, v0
	v_add_f32_e32 v0, 1.0, v16
	v_rcp_f32_e32 v16, v0
	v_add_f32_e32 v0, 1.0, v17
	v_rcp_f32_e32 v17, v0
	v_pk_mul_f32 v[6:7], v[6:7], v[12:13]
	v_lshlrev_b32_e32 v0, 11, v30
	s_waitcnt lgkmcnt(0)
	v_pk_mul_f32 v[6:7], v[8:9], v[6:7]
	v_pk_mul_f32 v[8:9], v[16:17], v[14:15]
	v_cvt_pk_bf16_f32 v6, v6, v7
	v_pk_mul_f32 v[8:9], v[10:11], v[8:9]
	v_lshl_add_u64 v[2:3], v[2:3], 0, v[0:1]
	v_cvt_pk_bf16_f32 v7, v8, v9
	global_store_dwordx4 v[2:3], v[4:7], off offset:1536
	s_barrier
	s_and_saveexec_b64 s[0:1], s[72:73]
	s_waitcnt vmcnt(4)
	v_mov_b32_e32 v0, s99
	v_mov_b32_e32 v141, v252
	ds_write_b32 v0, v141
